# v071 + U0 (GLU output of int8 in-projection) with padded 4224B rows; conformer conv reads it; CH/BG bases shifted
# baseline (speedup 1.0000x reference)
; __device__ __forceinline__ const char* unitA(const Gemm& g, const Unit& u) { return (const char*)(g.A + (size_t)(u.z / g.zdiv) * g.sAhi + (size_t)(u.z % g.zdiv) * g.sAlo + (size_t)u.pm * BM * g.lda); }
; __device__ __forceinline__ const char* unitB(const Gemm& g, const Unit& u) { return (const char*)(g.Bt + (size_t)(u.z / g.zdiv) * g.sBhi + (size_t)(u.z % g.zdiv) * g.sBlo + (size_t)(u.pm / g.bdiv) * g.sBpm + (size_t)u.pn * BM * g.ldb); }
; #define PG8_STAGE(bufoff, gbase, voff) do { if constexpr (VAR != 1 && VAR != 3) { _Pragma("unroll") for (int _i = 0; _i < 2; ++_i) \
;         asm volatile("s_mov_b32 m0, %2\n\ts_nop 0\n\tglobal_load_lds_dwordx4 %0, %1" :: "v"((voff)[_i]), "s"((const char*)(gbase)), "s"(ldsbase + (unsigned)((bufoff) + _i * 8192)) : "memory", "m0"); } } while (0)
; #define PG8_WAIT_V(n) asm volatile("s_waitcnt vmcnt(" #n ")" ::: "memory")
; #define PG8_BAR do { if constexpr (VAR != 3) __builtin_amdgcn_s_barrier(); } while (0)
;     ...
;     const char* cA = unitA(g, cur); const char* cB = unitB(g, cur);
;     PG8_STAGE(PG8_SB(0, 0), cB, voffB); PG8_STAGE(PG8_SB(0, 1), cB + hstepB, voffB); PG8_STAGE(PG8_SA(0, 0), cA, voffA); PG8_STAGE(PG8_SA(0, 1), cA + hstepA, voffA);
;     if (wr == 1) PG8_BAR;
;     PG8_WAIT_V(2); PG8_BAR;
;     PG8_STAGE(PG8_SB(1, 0), cB + kstep, voffB); PG8_STAGE(PG8_SA(1, 0), cA + kstep, voffA); PG8_STAGE(PG8_SB(1, 1), cB + hstepB + kstep, voffB);
;     PG8_WAIT_V(6); PG8_BAR;
; __global__ void __launch_bounds__(NWAVES * 64, 2) fwd_kernel(Args args) {
;     ...
;         { pg8::Gemm g{MEMN, WKV, DM, DM, DM, 1, 1 << 30, 0, 0, 0, 0, 0}; pg8::BatchOrder S; S.init(MMEM / 256, 2 * DM / 256, 1, G, vcu);
;           pg8::EpiBf16 E{KV, 2 * DM, nullptr, 1.0f, 1, 0, 0};
;           pg8::gemm_phase(ring, scr, g, S, E); }
.LBB0_336:
	v_readlane_b32 s36, v244, 2
	v_readlane_b32 s50, v244, 16
	v_readlane_b32 s51, v244, 17
	s_add_u32 s12, s50, 0x5100000
	s_addc_u32 s13, s51, 0
	s_add_u32 s58, s50, 0xd100000
	s_addc_u32 s59, s51, 0
	s_add_u32 s0, s50, 0x15100000
	s_addc_u32 s1, s51, 0
	s_add_u32 s8, s50, 0x26500000
	v_readlane_b32 s37, v244, 3
	v_readlane_b32 s38, v244, 4
	v_readlane_b32 s39, v244, 5
	v_readlane_b32 s40, v244, 6
	v_readlane_b32 s41, v244, 7
	v_readlane_b32 s42, v244, 8
	v_readlane_b32 s43, v244, 9
	v_readlane_b32 s44, v244, 10
	v_readlane_b32 s45, v244, 11
	v_readlane_b32 s46, v244, 12
	v_readlane_b32 s47, v244, 13
	v_readlane_b32 s48, v244, 14
	v_readlane_b32 s49, v244, 15
	v_writelane_b32 v244, s0, 45
	s_addc_u32 s9, s51, 0
	s_nop 0
	v_writelane_b32 v244, s1, 46
	s_add_u32 s0, s48, 0x4400000
	s_addc_u32 s1, s49, 0
	v_writelane_b32 v244, s0, 47
	s_nop 1
	v_writelane_b32 v244, s1, 48
	s_add_u32 s0, s48, 0x8800000
	s_addc_u32 s1, s49, 0
	v_writelane_b32 v244, s0, 49
	s_cmp_lt_i32 s96, 2
	s_nop 0
	v_writelane_b32 v244, s1, 50
	s_cselect_b64 s[0:1], -1, 0
	s_cmp_gt_i32 s97, 1
	s_cselect_b64 s[2:3], -1, 0
	s_and_b64 s[0:1], s[0:1], s[2:3]
	s_andn2_b64 vcc, exec, s[0:1]
	s_cbranch_vccnz .LBB0_626
	v_lshlrev_b32_e32 v130, 4, v0
	v_and_b32_e32 v1, 32, v0
	v_bitop3_b32 v1, v130, v1, 48 bitop3:0x6c
	s_waitcnt vmcnt(47)
	v_lshrrev_b32_e32 v4, 1, v0
	v_and_or_b32 v138, v0, 64, v1
	v_lshrrev_b32_e32 v1, 5, v0
	v_and_b32_e32 v144, 24, v4
	v_bfe_u32 v4, v0, 3, 25
	v_bfe_u32 v2, v0, 2, 4
	v_and_b32_e32 v1, 4, v1
	v_bfe_u32 v3, v0, 2, 2
	v_or_b32_e32 v4, 64, v4
	s_movk_i32 s0, 0x70
	v_or3_b32 v3, v1, v3, v144
	v_lshrrev_b32_e32 v1, 3, v0
	v_and_or_b32 v141, v4, s0, v2
	s_movk_i32 s0, 0x60
	v_readfirstlane_b32 s3, v0
	v_and_or_b32 v140, v1, 48, v2
	v_and_or_b32 v139, v1, 32, v3
	v_and_or_b32 v142, v4, s0, v3
	v_lshlrev_b32_e32 v2, 6, v0
	v_lshlrev_b32_e32 v3, 2, v0
	s_lshr_b32 s5, s3, 6
	v_lshlrev_b32_e32 v149, 1, v144
	v_and_b32_e32 v2, 0x3c0, v2
	v_and_b32_e32 v3, 32, v3
	v_and_b32_e32 v145, 15, v0
	v_lshl_or_b32 v1, v140, 13, v138
	v_lshl_or_b32 v146, v139, 13, v138
	v_lshl_or_b32 v147, v141, 13, v138
	v_lshl_or_b32 v148, v142, 13, v138
	s_cmpk_gt_i32 s34, 0x7f
	v_bitop3_b32 v150, v149, v3, v2 bitop3:0x36
	s_cbranch_scc1 .LBB0_353
	s_lshl_b32 s0, s5, 10
	v_readlane_b32 s36, v244, 2
	s_lshr_b32 s6, s3, 8
	s_add_i32 s19, s0, 0
	v_readlane_b32 s50, v244, 16
	v_readlane_b32 s51, v244, 17
	s_add_u32 s21, s50, 0x25d00000
	s_addc_u32 s23, s51, 0
	s_ashr_i32 s24, s34, 31
	s_lshr_b32 s0, s24, 25
	s_add_i32 s0, s34, s0
	s_and_b32 s0, s0, 0xff80
	s_sub_i32 s0, s34, s0
	s_bfe_i32 s1, s0, 0x80000
	s_bfe_u32 s1, s1, 0x5000a
	s_add_i32 s1, s0, s1
	s_bfe_i32 s2, s1, 0x80000
	s_and_b32 s1, s1, 0xffe0
	s_sext_i32_i16 s2, s2
	s_sub_i32 s4, s0, s1
	s_lshr_b32 s2, s2, 5
	s_bfe_i64 s[14:15], s[4:5], 0x80000
	s_bfe_i64 s[0:1], s[2:3], 0x100000
	s_lshl_b64 s[14:15], s[14:15], 21
	s_add_u32 s90, s86, s14
	s_addc_u32 s91, s87, s15
	s_add_i32 s25, s19, 0x10000
	s_mov_b32 m0, s25
	s_nop 0
	global_load_lds_dwordx4 v146, s[90:91]
	s_add_i32 s26, s19, 0x12000
	s_mov_b32 m0, s26
	s_nop 0
	global_load_lds_dwordx4 v148, s[90:91]
	s_add_u32 s14, s90, 0x100000
	s_addc_u32 s15, s91, 0
	s_add_i32 s27, s19, 0x14000
	s_mov_b32 m0, s27
	s_nop 0
	global_load_lds_dwordx4 v146, s[14:15]
	s_add_i32 s28, s19, 0x16000
	s_lshl_b64 s[0:1], s[0:1], 21
	s_mov_b32 m0, s28
	s_nop 0
	global_load_lds_dwordx4 v148, s[14:15]
	s_add_u32 s92, s21, s0
	s_addc_u32 s93, s23, s1
	s_mov_b32 m0, s19
	s_nop 0
	global_load_lds_dwordx4 v1, s[92:93]
	s_add_i32 s29, s19, 0x2000
	s_mov_b32 m0, s29
	s_nop 0
	global_load_lds_dwordx4 v147, s[92:93]
	s_add_u32 s14, s92, 0x100000
	s_addc_u32 s15, s93, 0
	s_add_i32 s30, s19, 0x4000
	s_mov_b32 m0, s30
	s_nop 0
	global_load_lds_dwordx4 v1, s[14:15]
	s_add_i32 s31, s19, 0x6000
	s_mov_b32 m0, s31
	s_nop 0
	global_load_lds_dwordx4 v147, s[14:15]
	s_cmp_eq_u32 s6, 1
	s_mov_b32 s17, 0
	s_cselect_b64 s[0:1], -1, 0
	s_cmp_lg_u32 s6, 1
	v_readlane_b32 s37, v244, 3
	v_readlane_b32 s38, v244, 4
	v_readlane_b32 s39, v244, 5
	v_readlane_b32 s40, v244, 6
	v_readlane_b32 s41, v244, 7
	v_readlane_b32 s42, v244, 8
	v_readlane_b32 s43, v244, 9
	v_readlane_b32 s44, v244, 10
	v_readlane_b32 s45, v244, 11
	v_readlane_b32 s46, v244, 12
	v_readlane_b32 s47, v244, 13
	v_readlane_b32 s48, v244, 14
	v_readlane_b32 s49, v244, 15
	s_cbranch_scc1 .LBB0_340
	s_barrier

; #define LAS __attribute__((address_space(3)))
; __device__ __forceinline__ unsigned cvt_pk_bf16(float lo, float hi) { unsigned r; asm volatile("v_cvt_pk_bf16_f32 %0, %1, %2" : "=v"(r) : "v"(lo), "v"(hi)); return r; }
;     __device__ __forceinline__ void operator()(EPI_ARGS) const {
;         const int row0 = u.pm * BM + wr * 64 + fr, c8 = wc * 32 + 8 * fq, pn = u.pn + pn_off;
;         if (I8) { if (__builtin_amdgcn_readfirstlane(((LAS int*)rtab)[256]) != u.pm) { EPI_BAR(); if (threadIdx.x < 256) rtab[threadIdx.x] = sA[u.pm * BM + threadIdx.x]; if (threadIdx.x == 0) ((LAS int*)rtab)[256] = u.pm; EPI_BAR(); } }
;         if (I8 || pn < 32) {
;             const bool glu = I8 || pn < 16;
;             bf16* base = (glu ? U0 : CH) + (size_t)((pn & 15) * HALF + c8);
;             f32x4 sb[2][2];
;             if (I8) {
; #pragma unroll
;                 for (int bj = 0; bj < 2; ++bj)
; #pragma unroll
;                     for (int n = 0; n < 2; ++n) { const u32x4 cm = *(const u32x4*)(cmaxB + pn * BM + bj * HALF + c8 + 4 * n); sb[bj][n] = (f32x4){__uint_as_float(cm.x), __uint_as_float(cm.y), __uint_as_float(cm.z), __uint_as_float(cm.w)} * (1.0f / 127.0f); } }
; #pragma unroll
;             for (int ai = 0; ai < 2; ++ai)
; #pragma unroll
;                 for (int m = 0; m < 4; ++m) {
;                     const float rs = I8 ? rtab[wr * 64 + fr + ai * HALF + m * 16] : 1.0f;
;                     f32x4 o[2];
; #pragma unroll
;                     for (int n = 0; n < 2; ++n) { f32x4 a = acc[ai][0][m][n], b = acc[ai][1][m][n];
;                         if (I8) { const i32x4 ia = __builtin_bit_cast(i32x4, a), ib = __builtin_bit_cast(i32x4, b);
;                             a = (f32x4){(float)ia[0], (float)ia[1], (float)ia[2], (float)ia[3]} * (sb[0][n] * rs); b = (f32x4){(float)ib[0], (float)ib[1], (float)ib[2], (float)ib[3]} * (sb[1][n] * rs); }
; #pragma unroll
;                         for (int e = 0; e < 4; ++e) o[n][e] = glu ? a[e] * fast_sigmoid(b[e]) : a[e] * b[e]; }
;                     u32x4 w; w.x = cvt_pk_bf16(o[0][0], o[0][1]); w.y = cvt_pk_bf16(o[0][2], o[0][3]); w.z = cvt_pk_bf16(o[1][0], o[1][1]); w.w = cvt_pk_bf16(o[1][2], o[1][3]);
;                     *(u32x4*)(base + (size_t)(row0 + ai * HALF + m * 16) * CWID) = w; }
.LBB0_548:
	s_lshl_b32 s10, s21, 8
	s_ashr_i32 s11, s10, 31
	v_lshl_add_u64 v[138:139], s[10:11], 2, v[132:133]
	global_load_dwordx4 v[164:167], v[138:139], off
	global_load_dwordx4 v[168:171], v[138:139], off offset:16
	global_load_dwordx4 v[172:175], v[138:139], off offset:512
	global_load_dwordx4 v[176:179], v[138:139], off offset:528
	ds_read_b32 v138, v158
	v_add_u32_e32 v140, s6, v155
	s_lshl_b32 s6, s21, 7
	v_cvt_f32_i32_e32 v139, v126
	v_cvt_f32_i32_e32 v182, v122
	v_cvt_f32_i32_e32 v183, v123
	s_and_b32 s6, s6, 0x780
	v_cvt_f32_i32_e32 v190, v114
	v_or_b32_e32 v114, s6, v157
	v_readlane_b32 s36, v244, 2
	v_cvt_f32_i32_e32 v141, v127
	v_cvt_f32_i32_e32 v180, v128
	v_cvt_f32_i32_e32 v181, v129
	v_lshlrev_b32_e32 v130, 1, v114
	v_readlane_b32 s48, v244, 14
	v_readlane_b32 s49, v244, 15
	v_cvt_f32_i32_e32 v184, v124
	v_cvt_f32_i32_e32 v185, v125
	v_lshl_add_u64 v[142:143], s[48:49], 0, v[130:131]
	v_cvt_f32_i32_e32 v186, v118
	v_cvt_f32_i32_e32 v187, v119
	v_cvt_f32_i32_e32 v191, v115
	v_cvt_f32_i32_e32 v192, v116
	v_cvt_f32_i32_e32 v193, v117
	v_cvt_f32_i32_e32 v188, v120
	v_cvt_f32_i32_e32 v189, v121
	v_cvt_f32_i32_e32 v106, v106
	v_cvt_f32_i32_e32 v110, v110
	v_cvt_f32_i32_e32 v107, v107
	v_cvt_f32_i32_e32 v111, v111
	v_cvt_f32_i32_e32 v108, v108
	v_cvt_f32_i32_e32 v109, v109
	v_cvt_f32_i32_e32 v98, v98
	v_cvt_f32_i32_e32 v99, v99
	v_cvt_f32_i32_e32 v112, v112
	v_cvt_f32_i32_e32 v113, v113
	v_cvt_f32_i32_e32 v102, v102
	v_cvt_f32_i32_e32 v103, v103
	v_cvt_f32_i32_e32 v100, v100
	v_cvt_f32_i32_e32 v101, v101
	v_cvt_f32_i32_e32 v104, v104
	v_cvt_f32_i32_e32 v105, v105
	v_cvt_f32_i32_e32 v90, v90
	v_cvt_f32_i32_e32 v94, v94
	v_cvt_f32_i32_e32 v91, v91
	v_cvt_f32_i32_e32 v95, v95
	v_cvt_f32_i32_e32 v92, v92
	v_cvt_f32_i32_e32 v93, v93
	v_cvt_f32_i32_e32 v82, v82
	v_cvt_f32_i32_e32 v83, v83
	v_cvt_f32_i32_e32 v96, v96
	v_cvt_f32_i32_e32 v97, v97
	v_cvt_f32_i32_e32 v86, v86
	v_cvt_f32_i32_e32 v87, v87
	v_cvt_f32_i32_e32 v84, v84
	v_cvt_f32_i32_e32 v85, v85
	v_cvt_f32_i32_e32 v88, v88
	v_cvt_f32_i32_e32 v89, v89
	v_cvt_f32_i32_e32 v74, v74
	v_cvt_f32_i32_e32 v78, v78
	v_cvt_f32_i32_e32 v75, v75
	v_cvt_f32_i32_e32 v79, v79
	v_cvt_f32_i32_e32 v76, v76
	v_cvt_f32_i32_e32 v77, v77
	v_cvt_f32_i32_e32 v66, v66
	v_cvt_f32_i32_e32 v67, v67
	v_cvt_f32_i32_e32 v80, v80
	v_cvt_f32_i32_e32 v81, v81
	v_cvt_f32_i32_e32 v70, v70
	v_cvt_f32_i32_e32 v71, v71
	v_cvt_f32_i32_e32 v68, v68
	v_cvt_f32_i32_e32 v69, v69
	v_cvt_f32_i32_e32 v72, v72
	v_cvt_f32_i32_e32 v73, v73
	v_cvt_f32_i32_e32 v58, v58
	v_cvt_f32_i32_e32 v62, v62
	s_waitcnt vmcnt(3)
	v_pk_mul_f32 v[126:127], v[164:165], s[68:69] op_sel_hi:[1,0]
	v_pk_mul_f32 v[122:123], v[166:167], s[68:69] op_sel_hi:[1,0]
	s_waitcnt vmcnt(1)
	v_pk_mul_f32 v[128:129], v[172:173], s[68:69] op_sel_hi:[1,0]
	s_waitcnt lgkmcnt(0)
	v_mul_f32_e32 v130, v126, v138
	v_mul_f32_e32 v164, v138, v128
	v_mul_f32_e32 v166, v138, v129
	v_mul_f32_e32 v130, v130, v139
	v_mul_f32_e32 v139, v164, v182
	v_mul_f32_e32 v164, v166, v183
	v_mul_f32_e32 v139, 0xbfb8aa3b, v139
	v_mul_f32_e32 v164, 0xbfb8aa3b, v164
	v_exp_f32_e32 v139, v139
	v_exp_f32_e32 v164, v164
	v_pk_mul_f32 v[124:125], v[174:175], s[68:69] op_sel_hi:[1,0]
	v_pk_mul_f32 v[114:115], v[170:171], s[68:69] op_sel_hi:[1,0]
	v_pk_mul_f32 v[118:119], v[168:169], s[68:69] op_sel_hi:[1,0]
	v_mul_f32_e32 v168, v138, v124
	v_mul_f32_e32 v170, v138, v125
	v_add_f32_e32 v139, 1.0, v139
	v_add_f32_e32 v164, 1.0, v164
	v_mul_f32_e32 v166, v168, v184
	v_mul_f32_e32 v168, v170, v185
	v_rcp_f32_e32 v139, v139
	v_rcp_f32_e32 v164, v164
	v_mul_f32_e32 v166, 0xbfb8aa3b, v166
	v_mul_f32_e32 v168, 0xbfb8aa3b, v168
	s_waitcnt vmcnt(0)
	v_pk_mul_f32 v[120:121], v[176:177], s[68:69] op_sel_hi:[1,0]
	v_mul_f32_e32 v165, v127, v138
	v_exp_f32_e32 v166, v166
	v_exp_f32_e32 v168, v168
	v_pk_mul_f32 v[116:117], v[178:179], s[68:69] op_sel_hi:[1,0]
	v_mul_f32_e32 v172, v138, v120
	v_mul_f32_e32 v174, v138, v121
	v_mul_f32_e32 v141, v165, v141
	v_mul_f32_e32 v167, v122, v138
	v_mul_f32_e32 v169, v123, v138
	v_mul_f32_e32 v171, v118, v138
	v_mul_f32_e32 v173, v119, v138
	v_mul_f32_e32 v176, v138, v116
	v_mul_f32_e32 v170, v172, v190
	v_mul_f32_e32 v172, v174, v191
	v_mul_f32_e32 v130, v130, v139
	v_mul_f32_e32 v139, v141, v164
	v_mul_f32_e32 v164, v138, v117
	v_mul_f32_e32 v165, v167, v180
	v_mul_f32_e32 v167, v169, v181
	v_mul_f32_e32 v169, v171, v186
	v_mul_f32_e32 v171, v173, v187
	v_mul_f32_e32 v173, v176, v192
	v_mul_f32_e32 v170, 0xbfb8aa3b, v170
	v_mul_f32_e32 v172, 0xbfb8aa3b, v172
	v_mul_f32_e32 v164, v164, v193
	v_mul_f32_e32 v173, 0xbfb8aa3b, v173
	v_exp_f32_e32 v170, v170
	v_exp_f32_e32 v172, v172
	v_add_f32_e32 v166, 1.0, v166
	v_add_f32_e32 v168, 1.0, v168
	v_mul_f32_e32 v164, 0xbfb8aa3b, v164
	v_exp_f32_e32 v173, v173
	v_rcp_f32_e32 v166, v166
	v_rcp_f32_e32 v168, v168
	v_exp_f32_e32 v164, v164
	v_add_f32_e32 v170, 1.0, v170
	v_add_f32_e32 v172, 1.0, v172
	v_rcp_f32_e32 v170, v170
	v_rcp_f32_e32 v172, v172
	v_mul_f32_e32 v141, v165, v166
	v_mul_f32_e32 v165, v167, v168
	v_add_f32_e32 v168, 1.0, v173
	v_add_f32_e32 v164, 1.0, v164
	v_rcp_f32_e32 v168, v168
	v_rcp_f32_e32 v164, v164
	v_mul_f32_e32 v175, v114, v138
	v_mul_f32_e32 v138, v115, v138
	v_mul_f32_e32 v166, v169, v170
	v_mul_f32_e32 v167, v171, v172
	v_mul_f32_e32 v169, v175, v188
	v_mul_f32_e32 v138, v138, v189
	v_mul_f32_e32 v168, v169, v168
	v_mul_f32_e32 v138, v138, v164
	v_cvt_pk_bf16_f32 v164, v130, v139
	v_cvt_pk_bf16_f32 v165, v141, v165
	v_cvt_pk_bf16_f32 v166, v166, v167
	v_cvt_pk_bf16_f32 v167, v168, v138
	ds_read_b32 v130, v158 offset:64
	v_ashrrev_i32_e32 v141, 31, v140
	v_mul_u32_u24_e32 v138, 0x1080, v140
	v_mov_b32_e32 v139, 0
	v_lshl_add_u64 v[138:139], v[142:143], 0, v[138:139]
	global_store_dwordx4 v[138:139], v[164:167], off
	s_waitcnt lgkmcnt(0)
; __device__ __forceinline__ unsigned cvt_pk_bf16(float lo, float hi) { unsigned r; asm volatile("v_cvt_pk_bf16_f32 %0, %1, %2" : "=v"(r) : "v"(lo), "v"(hi)); return r; }
; __device__ __forceinline__ float fast_sigmoid(float x) { return __builtin_amdgcn_rcpf(1.0f + __builtin_amdgcn_exp2f(-x * LOG2E)); }
;     __device__ __forceinline__ void operator()(EPI_ARGS) const {
;     ...
; #pragma unroll
;             for (int ai = 0; ai < 2; ++ai)
; #pragma unroll
;                 for (int m = 0; m < 4; ++m) {
;                     const float rs = I8 ? rtab[wr * 64 + fr + ai * HALF + m * 16] : 1.0f;
;                     f32x4 o[2];
; #pragma unroll
;                     for (int n = 0; n < 2; ++n) { f32x4 a = acc[ai][0][m][n], b = acc[ai][1][m][n];
;                         if (I8) { const i32x4 ia = __builtin_bit_cast(i32x4, a), ib = __builtin_bit_cast(i32x4, b);
;                             a = (f32x4){(float)ia[0], (float)ia[1], (float)ia[2], (float)ia[3]} * (sb[0][n] * rs); b = (f32x4){(float)ib[0], (float)ib[1], (float)ib[2], (float)ib[3]} * (sb[1][n] * rs); }
; #pragma unroll
;                         for (int e = 0; e < 4; ++e) o[n][e] = glu ? a[e] * fast_sigmoid(b[e]) : a[e] * b[e]; }
;                     u32x4 w; w.x = cvt_pk_bf16(o[0][0], o[0][1]); w.y = cvt_pk_bf16(o[0][2], o[0][3]); w.z = cvt_pk_bf16(o[1][0], o[1][1]); w.w = cvt_pk_bf16(o[1][2], o[1][3]);
;                     *(u32x4*)(base + (size_t)(row0 + ai * HALF + m * 16) * CWID) = w; }
	v_mul_f32_e32 v141, v126, v130
	v_mul_f32_e32 v110, v141, v110
	v_mul_f32_e32 v164, v128, v130
	v_mul_f32_e32 v106, v164, v106
	v_mul_f32_e32 v106, 0xbfb8aa3b, v106
	v_exp_f32_e32 v106, v106
	v_mul_f32_e32 v164, v129, v130
	v_mul_f32_e32 v107, v164, v107
	v_mul_f32_e32 v107, 0xbfb8aa3b, v107
	v_add_f32_e32 v106, 1.0, v106
	v_rcp_f32_e32 v106, v106
	v_exp_f32_e32 v107, v107
	v_cvt_f32_i32_e32 v59, v59
	v_cvt_f32_i32_e32 v63, v63
	v_mul_f32_e32 v106, v110, v106
	v_mul_f32_e32 v110, v127, v130
	v_mul_f32_e32 v110, v110, v111
	v_mul_f32_e32 v111, v124, v130
	v_mul_f32_e32 v108, v111, v108
	v_mul_f32_e32 v108, 0xbfb8aa3b, v108
	v_mul_f32_e32 v111, v125, v130
	v_exp_f32_e32 v108, v108
	v_mul_f32_e32 v109, v111, v109
	v_mul_f32_e32 v109, 0xbfb8aa3b, v109
	v_mul_f32_e32 v111, v120, v130
	v_add_f32_e32 v107, 1.0, v107
	v_exp_f32_e32 v109, v109
	v_mul_f32_e32 v98, v111, v98
	v_rcp_f32_e32 v107, v107
	v_mul_f32_e32 v98, 0xbfb8aa3b, v98
	v_mul_f32_e32 v111, v121, v130
	v_add_f32_e32 v108, 1.0, v108
	v_exp_f32_e32 v98, v98
	v_mul_f32_e32 v99, v111, v99
	v_rcp_f32_e32 v108, v108
	v_mul_f32_e32 v99, 0xbfb8aa3b, v99
	v_add_f32_e32 v109, 1.0, v109
	v_exp_f32_e32 v99, v99
	v_mul_f32_e32 v107, v110, v107
	v_mul_f32_e32 v110, v122, v130
	v_rcp_f32_e32 v109, v109
	v_mul_f32_e32 v110, v110, v112
	v_add_f32_e32 v98, 1.0, v98
	v_mul_f32_e32 v108, v110, v108
	v_mul_f32_e32 v110, v123, v130
	v_rcp_f32_e32 v98, v98
	v_mul_f32_e32 v110, v110, v113
	v_add_f32_e32 v99, 1.0, v99
	v_mul_f32_e32 v109, v110, v109
	v_mul_f32_e32 v110, v118, v130
	v_rcp_f32_e32 v99, v99
	v_mul_f32_e32 v102, v110, v102
	v_mul_f32_e32 v102, v102, v98
	v_mul_f32_e32 v98, v119, v130
	v_mul_f32_e32 v98, v98, v103
	v_mul_f32_e32 v103, v98, v99
	v_mul_f32_e32 v99, v116, v130
	v_mul_f32_e32 v99, v99, v100
	v_mul_f32_e32 v99, 0xbfb8aa3b, v99
	v_mul_f32_e32 v100, v117, v130
	v_exp_f32_e32 v99, v99
	v_mul_f32_e32 v100, v100, v101
	v_mul_f32_e32 v100, 0xbfb8aa3b, v100
	v_exp_f32_e32 v100, v100
	v_add_f32_e32 v99, 1.0, v99
	v_rcp_f32_e32 v99, v99
	v_mul_f32_e32 v98, v114, v130
	v_add_f32_e32 v100, 1.0, v100
	v_rcp_f32_e32 v100, v100
	v_mul_f32_e32 v98, v98, v104
	v_mul_f32_e32 v101, v98, v99
	v_mul_f32_e32 v98, v115, v130
	v_mul_f32_e32 v98, v98, v105
	v_mul_f32_e32 v104, v98, v100
	v_cvt_pk_bf16_f32 v98, v106, v107
	v_cvt_pk_bf16_f32 v99, v108, v109
	v_cvt_pk_bf16_f32 v100, v102, v103
	v_or_b32_e32 v102, 16, v140
	v_ashrrev_i32_e32 v103, 31, v102
	v_mul_u32_u24_e32 v102, 0x1080, v102
	v_mov_b32_e32 v103, 0
	v_lshl_add_u64 v[102:103], v[142:143], 0, v[102:103]
	v_cvt_pk_bf16_f32 v101, v101, v104
	global_store_dwordx4 v[102:103], v[98:101], off
	ds_read_b32 v98, v158 offset:128
	v_cvt_f32_i32_e32 v60, v60
	v_cvt_f32_i32_e32 v61, v61
	v_cvt_f32_i32_e32 v50, v50
	v_cvt_f32_i32_e32 v51, v51
	s_waitcnt lgkmcnt(0)
	v_mul_f32_e32 v100, v128, v98
	v_mul_f32_e32 v90, v100, v90
	v_mul_f32_e32 v90, 0xbfb8aa3b, v90
	v_exp_f32_e32 v90, v90
	v_mul_f32_e32 v99, v126, v98
	v_mul_f32_e32 v100, v129, v98
	v_mul_f32_e32 v94, v99, v94
	v_add_f32_e32 v90, 1.0, v90
	v_rcp_f32_e32 v90, v90
	v_mul_f32_e32 v91, v100, v91
	v_mul_f32_e32 v91, 0xbfb8aa3b, v91
	v_exp_f32_e32 v91, v91
	v_mul_f32_e32 v90, v94, v90
	v_mul_f32_e32 v94, v127, v98
	v_mul_f32_e32 v94, v94, v95
	v_mul_f32_e32 v95, v124, v98
	v_mul_f32_e32 v92, v95, v92
	v_mul_f32_e32 v92, 0xbfb8aa3b, v92
	v_mul_f32_e32 v95, v125, v98
	v_exp_f32_e32 v92, v92
	v_mul_f32_e32 v93, v95, v93
	v_mul_f32_e32 v93, 0xbfb8aa3b, v93
	v_mul_f32_e32 v95, v120, v98
	v_add_f32_e32 v91, 1.0, v91
	v_exp_f32_e32 v93, v93
	v_mul_f32_e32 v82, v95, v82
	v_rcp_f32_e32 v91, v91
	v_mul_f32_e32 v82, 0xbfb8aa3b, v82
	v_mul_f32_e32 v95, v121, v98
	v_add_f32_e32 v92, 1.0, v92
	v_exp_f32_e32 v82, v82
	v_mul_f32_e32 v83, v95, v83
	v_rcp_f32_e32 v92, v92
	v_mul_f32_e32 v83, 0xbfb8aa3b, v83
	v_add_f32_e32 v93, 1.0, v93
	v_exp_f32_e32 v83, v83
	v_mul_f32_e32 v91, v94, v91
	v_mul_f32_e32 v94, v122, v98
	v_rcp_f32_e32 v93, v93
	v_mul_f32_e32 v94, v94, v96
	v_add_f32_e32 v82, 1.0, v82
	v_mul_f32_e32 v92, v94, v92
	v_mul_f32_e32 v94, v123, v98
	v_rcp_f32_e32 v82, v82
	v_mul_f32_e32 v94, v94, v97
	v_add_f32_e32 v83, 1.0, v83
	v_mul_f32_e32 v93, v94, v93
	v_mul_f32_e32 v94, v118, v98
	v_rcp_f32_e32 v83, v83
	v_mul_f32_e32 v86, v94, v86
	v_mul_f32_e32 v86, v86, v82
	v_mul_f32_e32 v82, v119, v98
	v_mul_f32_e32 v82, v82, v87
	v_mul_f32_e32 v87, v82, v83
	v_mul_f32_e32 v83, v116, v98
	v_mul_f32_e32 v83, v83, v84
	v_mul_f32_e32 v83, 0xbfb8aa3b, v83
	v_mul_f32_e32 v84, v117, v98
	v_exp_f32_e32 v83, v83
	v_mul_f32_e32 v84, v84, v85
	v_mul_f32_e32 v84, 0xbfb8aa3b, v84
	v_exp_f32_e32 v84, v84
	v_add_f32_e32 v83, 1.0, v83
	v_rcp_f32_e32 v83, v83
	v_mul_f32_e32 v82, v114, v98
	v_add_f32_e32 v84, 1.0, v84
	v_rcp_f32_e32 v84, v84
	v_mul_f32_e32 v82, v82, v88
	v_mul_f32_e32 v85, v82, v83
	v_mul_f32_e32 v82, v115, v98
	v_mul_f32_e32 v82, v82, v89
	v_mul_f32_e32 v88, v82, v84
	v_cvt_pk_bf16_f32 v82, v90, v91
	v_cvt_pk_bf16_f32 v83, v92, v93
	v_cvt_pk_bf16_f32 v84, v86, v87
	v_or_b32_e32 v86, 32, v140
	v_ashrrev_i32_e32 v87, 31, v86
	v_mul_u32_u24_e32 v86, 0x1080, v86
	v_mov_b32_e32 v87, 0
	v_lshl_add_u64 v[86:87], v[142:143], 0, v[86:87]
	v_cvt_pk_bf16_f32 v85, v85, v88
	global_store_dwordx4 v[86:87], v[82:85], off
	ds_read_b32 v82, v158 offset:192
	v_cvt_f32_i32_e32 v64, v64
	v_cvt_f32_i32_e32 v65, v65
	v_cvt_f32_i32_e32 v54, v54
	v_cvt_f32_i32_e32 v55, v55
	s_waitcnt lgkmcnt(0)
; __device__ __forceinline__ unsigned cvt_pk_bf16(float lo, float hi) { unsigned r; asm volatile("v_cvt_pk_bf16_f32 %0, %1, %2" : "=v"(r) : "v"(lo), "v"(hi)); return r; }
; __device__ __forceinline__ float fast_sigmoid(float x) { return __builtin_amdgcn_rcpf(1.0f + __builtin_amdgcn_exp2f(-x * LOG2E)); }
;     __device__ __forceinline__ void operator()(EPI_ARGS) const {
;     ...
; #pragma unroll
;             for (int ai = 0; ai < 2; ++ai)
; #pragma unroll
;                 for (int m = 0; m < 4; ++m) {
;                     const float rs = I8 ? rtab[wr * 64 + fr + ai * HALF + m * 16] : 1.0f;
;                     f32x4 o[2];
; #pragma unroll
;                     for (int n = 0; n < 2; ++n) { f32x4 a = acc[ai][0][m][n], b = acc[ai][1][m][n];
;                         if (I8) { const i32x4 ia = __builtin_bit_cast(i32x4, a), ib = __builtin_bit_cast(i32x4, b);
;                             a = (f32x4){(float)ia[0], (float)ia[1], (float)ia[2], (float)ia[3]} * (sb[0][n] * rs); b = (f32x4){(float)ib[0], (float)ib[1], (float)ib[2], (float)ib[3]} * (sb[1][n] * rs); }
; #pragma unroll
;                         for (int e = 0; e < 4; ++e) o[n][e] = glu ? a[e] * fast_sigmoid(b[e]) : a[e] * b[e]; }
;                     u32x4 w; w.x = cvt_pk_bf16(o[0][0], o[0][1]); w.y = cvt_pk_bf16(o[0][2], o[0][3]); w.z = cvt_pk_bf16(o[1][0], o[1][1]); w.w = cvt_pk_bf16(o[1][2], o[1][3]);
;                     *(u32x4*)(base + (size_t)(row0 + ai * HALF + m * 16) * CWID) = w; }
	v_mul_f32_e32 v84, v128, v82
	v_mul_f32_e32 v74, v84, v74
	v_mul_f32_e32 v74, 0xbfb8aa3b, v74
	v_exp_f32_e32 v74, v74
	v_mul_f32_e32 v83, v126, v82
	v_mul_f32_e32 v84, v129, v82
	v_mul_f32_e32 v78, v83, v78
	v_add_f32_e32 v74, 1.0, v74
	v_rcp_f32_e32 v74, v74
	v_mul_f32_e32 v75, v84, v75
	v_mul_f32_e32 v75, 0xbfb8aa3b, v75
	v_exp_f32_e32 v75, v75
	v_mul_f32_e32 v74, v78, v74
	v_mul_f32_e32 v78, v127, v82
	v_mul_f32_e32 v78, v78, v79
	v_mul_f32_e32 v79, v124, v82
	v_mul_f32_e32 v76, v79, v76
	v_mul_f32_e32 v76, 0xbfb8aa3b, v76
	v_mul_f32_e32 v79, v125, v82
	v_exp_f32_e32 v76, v76
	v_mul_f32_e32 v77, v79, v77
	v_mul_f32_e32 v77, 0xbfb8aa3b, v77
	v_mul_f32_e32 v79, v120, v82
	v_add_f32_e32 v75, 1.0, v75
	v_exp_f32_e32 v77, v77
	v_mul_f32_e32 v66, v79, v66
	v_rcp_f32_e32 v75, v75
	v_mul_f32_e32 v66, 0xbfb8aa3b, v66
	v_mul_f32_e32 v79, v121, v82
	v_add_f32_e32 v76, 1.0, v76
	v_exp_f32_e32 v66, v66
	v_mul_f32_e32 v67, v79, v67
	v_rcp_f32_e32 v76, v76
	v_mul_f32_e32 v67, 0xbfb8aa3b, v67
	v_add_f32_e32 v77, 1.0, v77
	v_exp_f32_e32 v67, v67
	v_mul_f32_e32 v75, v78, v75
	v_mul_f32_e32 v78, v122, v82
	v_rcp_f32_e32 v77, v77
	v_mul_f32_e32 v78, v78, v80
	v_add_f32_e32 v66, 1.0, v66
	v_mul_f32_e32 v76, v78, v76
	v_mul_f32_e32 v78, v123, v82
	v_rcp_f32_e32 v66, v66
	v_mul_f32_e32 v78, v78, v81
	v_add_f32_e32 v67, 1.0, v67
	v_mul_f32_e32 v77, v78, v77
	v_mul_f32_e32 v78, v118, v82
	v_rcp_f32_e32 v67, v67
	v_mul_f32_e32 v70, v78, v70
	v_mul_f32_e32 v70, v70, v66
	v_mul_f32_e32 v66, v119, v82
	v_mul_f32_e32 v66, v66, v71
	v_mul_f32_e32 v71, v66, v67
	v_mul_f32_e32 v67, v116, v82
	v_mul_f32_e32 v67, v67, v68
	v_mul_f32_e32 v67, 0xbfb8aa3b, v67
	v_mul_f32_e32 v68, v117, v82
	v_exp_f32_e32 v67, v67
	v_mul_f32_e32 v68, v68, v69
	v_mul_f32_e32 v68, 0xbfb8aa3b, v68
	v_exp_f32_e32 v68, v68
	v_add_f32_e32 v67, 1.0, v67
	v_rcp_f32_e32 v67, v67
	v_mul_f32_e32 v66, v114, v82
	v_add_f32_e32 v68, 1.0, v68
	v_rcp_f32_e32 v68, v68
	v_mul_f32_e32 v66, v66, v72
	v_mul_f32_e32 v69, v66, v67
	v_mul_f32_e32 v66, v115, v82
	v_mul_f32_e32 v66, v66, v73
	v_mul_f32_e32 v72, v66, v68
	v_cvt_pk_bf16_f32 v66, v74, v75
	v_cvt_pk_bf16_f32 v67, v76, v77
	v_cvt_pk_bf16_f32 v68, v70, v71
	v_or_b32_e32 v70, 48, v140
	v_ashrrev_i32_e32 v71, 31, v70
	v_mul_u32_u24_e32 v70, 0x1080, v70
	v_mov_b32_e32 v71, 0
	v_lshl_add_u64 v[70:71], v[142:143], 0, v[70:71]
	v_cvt_pk_bf16_f32 v69, v69, v72
	global_store_dwordx4 v[70:71], v[66:69], off
	ds_read_b32 v66, v158 offset:512
	v_cvt_f32_i32_e32 v52, v52
	v_cvt_f32_i32_e32 v53, v53
	v_cvt_f32_i32_e32 v56, v56
	v_cvt_f32_i32_e32 v57, v57
	s_waitcnt lgkmcnt(0)
	v_mul_f32_e32 v68, v128, v66
	v_mul_f32_e32 v58, v68, v58
	v_mul_f32_e32 v58, 0xbfb8aa3b, v58
	v_exp_f32_e32 v58, v58
	v_mul_f32_e32 v67, v126, v66
	v_mul_f32_e32 v68, v129, v66
	v_mul_f32_e32 v62, v67, v62
	v_add_f32_e32 v58, 1.0, v58
	v_rcp_f32_e32 v58, v58
	v_mul_f32_e32 v59, v68, v59
	v_mul_f32_e32 v59, 0xbfb8aa3b, v59
	v_exp_f32_e32 v59, v59
	v_mul_f32_e32 v58, v62, v58
	v_mul_f32_e32 v62, v127, v66
	v_mul_f32_e32 v62, v62, v63
	v_mul_f32_e32 v63, v124, v66
	v_mul_f32_e32 v60, v63, v60
	v_mul_f32_e32 v60, 0xbfb8aa3b, v60
	v_mul_f32_e32 v63, v125, v66
	v_exp_f32_e32 v60, v60
	v_mul_f32_e32 v61, v63, v61
	v_mul_f32_e32 v61, 0xbfb8aa3b, v61
	v_mul_f32_e32 v63, v120, v66
	v_add_f32_e32 v59, 1.0, v59
	v_exp_f32_e32 v61, v61
	v_mul_f32_e32 v50, v63, v50
	v_rcp_f32_e32 v59, v59
	v_mul_f32_e32 v50, 0xbfb8aa3b, v50
	v_mul_f32_e32 v63, v121, v66
	v_add_f32_e32 v60, 1.0, v60
	v_exp_f32_e32 v50, v50
	v_mul_f32_e32 v51, v63, v51
	v_rcp_f32_e32 v60, v60
	v_mul_f32_e32 v51, 0xbfb8aa3b, v51
	v_add_f32_e32 v61, 1.0, v61
	v_exp_f32_e32 v51, v51
	v_mul_f32_e32 v59, v62, v59
	v_mul_f32_e32 v62, v122, v66
	v_rcp_f32_e32 v61, v61
	v_mul_f32_e32 v62, v62, v64
	v_add_f32_e32 v50, 1.0, v50
	v_mul_f32_e32 v60, v62, v60
	v_mul_f32_e32 v62, v123, v66
	v_rcp_f32_e32 v50, v50
	v_mul_f32_e32 v62, v62, v65
	v_add_f32_e32 v51, 1.0, v51
	v_mul_f32_e32 v61, v62, v61
	v_mul_f32_e32 v62, v118, v66
	v_rcp_f32_e32 v51, v51
	v_mul_f32_e32 v54, v62, v54
	v_mul_f32_e32 v54, v54, v50
	v_mul_f32_e32 v50, v119, v66
	v_mul_f32_e32 v50, v50, v55
	v_mul_f32_e32 v55, v50, v51
	v_mul_f32_e32 v51, v116, v66
	v_mul_f32_e32 v51, v51, v52
	v_mul_f32_e32 v51, 0xbfb8aa3b, v51
	v_mul_f32_e32 v52, v117, v66
	v_exp_f32_e32 v51, v51
	v_mul_f32_e32 v52, v52, v53
	v_mul_f32_e32 v52, 0xbfb8aa3b, v52
	v_exp_f32_e32 v52, v52
	v_add_f32_e32 v51, 1.0, v51
	v_rcp_f32_e32 v51, v51
	v_mul_f32_e32 v50, v114, v66
	v_add_f32_e32 v52, 1.0, v52
	v_rcp_f32_e32 v52, v52
	v_mul_f32_e32 v50, v50, v56
	v_mul_f32_e32 v53, v50, v51
	v_mul_f32_e32 v50, v115, v66
	v_mul_f32_e32 v50, v50, v57
	s_mov_b32 s6, 0x84000
	v_mul_f32_e32 v56, v50, v52
	v_cvt_pk_bf16_f32 v50, v58, v59
	v_cvt_pk_bf16_f32 v51, v60, v61
	v_cvt_pk_bf16_f32 v52, v54, v55
	v_add_co_u32_e32 v54, vcc, s6, v138
	v_cvt_pk_bf16_f32 v53, v53, v56
	v_cvt_f32_i32_e32 v42, v42
	s_nop 0
	v_addc_co_u32_e32 v55, vcc, 0, v139, vcc
	global_store_dwordx4 v[54:55], v[50:53], off
	ds_read_b32 v50, v158 offset:576
	v_cvt_f32_i32_e32 v46, v46
	v_cvt_f32_i32_e32 v43, v43
	v_cvt_f32_i32_e32 v47, v47
	v_cvt_f32_i32_e32 v44, v44
	s_waitcnt lgkmcnt(0)
; __device__ __forceinline__ unsigned cvt_pk_bf16(float lo, float hi) { unsigned r; asm volatile("v_cvt_pk_bf16_f32 %0, %1, %2" : "=v"(r) : "v"(lo), "v"(hi)); return r; }
; __device__ __forceinline__ float fast_sigmoid(float x) { return __builtin_amdgcn_rcpf(1.0f + __builtin_amdgcn_exp2f(-x * LOG2E)); }
;     __device__ __forceinline__ void operator()(EPI_ARGS) const {
;     ...
; #pragma unroll
;             for (int ai = 0; ai < 2; ++ai)
; #pragma unroll
;                 for (int m = 0; m < 4; ++m) {
;                     const float rs = I8 ? rtab[wr * 64 + fr + ai * HALF + m * 16] : 1.0f;
;                     f32x4 o[2];
; #pragma unroll
;                     for (int n = 0; n < 2; ++n) { f32x4 a = acc[ai][0][m][n], b = acc[ai][1][m][n];
;                         if (I8) { const i32x4 ia = __builtin_bit_cast(i32x4, a), ib = __builtin_bit_cast(i32x4, b);
;                             a = (f32x4){(float)ia[0], (float)ia[1], (float)ia[2], (float)ia[3]} * (sb[0][n] * rs); b = (f32x4){(float)ib[0], (float)ib[1], (float)ib[2], (float)ib[3]} * (sb[1][n] * rs); }
; #pragma unroll
;                         for (int e = 0; e < 4; ++e) o[n][e] = glu ? a[e] * fast_sigmoid(b[e]) : a[e] * b[e]; }
;                     u32x4 w; w.x = cvt_pk_bf16(o[0][0], o[0][1]); w.y = cvt_pk_bf16(o[0][2], o[0][3]); w.z = cvt_pk_bf16(o[1][0], o[1][1]); w.w = cvt_pk_bf16(o[1][2], o[1][3]);
;                     *(u32x4*)(base + (size_t)(row0 + ai * HALF + m * 16) * CWID) = w; }
	v_mul_f32_e32 v52, v128, v50
	v_mul_f32_e32 v42, v52, v42
	v_mul_f32_e32 v42, 0xbfb8aa3b, v42
	v_exp_f32_e32 v42, v42
	v_mul_f32_e32 v51, v126, v50
	v_mul_f32_e32 v52, v129, v50
	v_mul_f32_e32 v46, v51, v46
	v_add_f32_e32 v42, 1.0, v42
	v_rcp_f32_e32 v42, v42
	v_cvt_f32_i32_e32 v45, v45
	v_mul_f32_e32 v43, v52, v43
	v_mul_f32_e32 v43, 0xbfb8aa3b, v43
	v_mul_f32_e32 v42, v46, v42
	v_mul_f32_e32 v46, v127, v50
	v_mul_f32_e32 v46, v46, v47
	v_mul_f32_e32 v47, v124, v50
	v_exp_f32_e32 v43, v43
	v_mul_f32_e32 v44, v47, v44
	v_cvt_f32_i32_e32 v34, v34
	v_mul_f32_e32 v44, 0xbfb8aa3b, v44
	v_mul_f32_e32 v47, v125, v50
	v_exp_f32_e32 v44, v44
	v_mul_f32_e32 v45, v47, v45
	v_cvt_f32_i32_e32 v35, v35
	v_mul_f32_e32 v45, 0xbfb8aa3b, v45
	v_mul_f32_e32 v47, v120, v50
	v_add_f32_e32 v43, 1.0, v43
	v_exp_f32_e32 v45, v45
	v_mul_f32_e32 v34, v47, v34
	v_rcp_f32_e32 v43, v43
	v_mul_f32_e32 v34, 0xbfb8aa3b, v34
	v_mul_f32_e32 v47, v121, v50
	v_cvt_f32_i32_e32 v48, v48
	v_add_f32_e32 v44, 1.0, v44
	v_exp_f32_e32 v34, v34
	v_mul_f32_e32 v35, v47, v35
	v_rcp_f32_e32 v44, v44
	v_mul_f32_e32 v35, 0xbfb8aa3b, v35
	v_cvt_f32_i32_e32 v49, v49
	v_add_f32_e32 v45, 1.0, v45
	v_exp_f32_e32 v35, v35
	v_mul_f32_e32 v43, v46, v43
	v_mul_f32_e32 v46, v122, v50
	v_rcp_f32_e32 v45, v45
	v_mul_f32_e32 v46, v46, v48
	v_cvt_f32_i32_e32 v38, v38
	v_add_f32_e32 v34, 1.0, v34
	v_mul_f32_e32 v44, v46, v44
	v_mul_f32_e32 v46, v123, v50
	v_rcp_f32_e32 v34, v34
	v_mul_f32_e32 v46, v46, v49
	v_cvt_f32_i32_e32 v39, v39
	v_add_f32_e32 v35, 1.0, v35
	v_mul_f32_e32 v45, v46, v45
	v_mul_f32_e32 v46, v118, v50
	v_rcp_f32_e32 v35, v35
	v_cvt_f32_i32_e32 v36, v36
	v_mul_f32_e32 v38, v46, v38
	v_mul_f32_e32 v38, v38, v34
	v_mul_f32_e32 v34, v119, v50
	v_cvt_f32_i32_e32 v37, v37
	v_mul_f32_e32 v34, v34, v39
	v_mul_f32_e32 v39, v34, v35
	v_mul_f32_e32 v35, v116, v50
	v_mul_f32_e32 v35, v35, v36
	v_mul_f32_e32 v35, 0xbfb8aa3b, v35
	v_mul_f32_e32 v36, v117, v50
	v_exp_f32_e32 v35, v35
	v_mul_f32_e32 v36, v36, v37
	v_mul_f32_e32 v36, 0xbfb8aa3b, v36
	v_exp_f32_e32 v36, v36
	v_cvt_f32_i32_e32 v40, v40
	v_add_f32_e32 v35, 1.0, v35
	v_rcp_f32_e32 v35, v35
	v_cvt_f32_i32_e32 v41, v41
	v_add_f32_e32 v36, 1.0, v36
	v_mul_f32_e32 v34, v114, v50
	v_rcp_f32_e32 v36, v36
	v_mul_f32_e32 v34, v34, v40
	v_mul_f32_e32 v37, v34, v35
	v_mul_f32_e32 v34, v115, v50
	v_mul_f32_e32 v34, v34, v41
	s_mov_b32 s6, 0x94800
	v_mul_f32_e32 v40, v34, v36
	v_cvt_pk_bf16_f32 v34, v42, v43
	v_cvt_pk_bf16_f32 v35, v44, v45
	v_cvt_pk_bf16_f32 v36, v38, v39
	v_add_co_u32_e32 v38, vcc, s6, v138
	v_cvt_pk_bf16_f32 v37, v37, v40
	v_cvt_f32_i32_e32 v26, v26
	s_nop 0
	v_addc_co_u32_e32 v39, vcc, 0, v139, vcc
	global_store_dwordx4 v[38:39], v[34:37], off
	ds_read_b32 v34, v158 offset:640
	v_cvt_f32_i32_e32 v30, v30
	v_cvt_f32_i32_e32 v27, v27
	v_cvt_f32_i32_e32 v31, v31
	v_cvt_f32_i32_e32 v28, v28
	s_waitcnt lgkmcnt(0)
	v_mul_f32_e32 v36, v128, v34
	v_mul_f32_e32 v26, v36, v26
	v_mul_f32_e32 v26, 0xbfb8aa3b, v26
	v_exp_f32_e32 v26, v26
	v_mul_f32_e32 v35, v126, v34
	v_mul_f32_e32 v36, v129, v34
	v_mul_f32_e32 v30, v35, v30
	v_add_f32_e32 v26, 1.0, v26
	v_rcp_f32_e32 v26, v26
	v_cvt_f32_i32_e32 v29, v29
	v_mul_f32_e32 v27, v36, v27
	v_mul_f32_e32 v27, 0xbfb8aa3b, v27
	v_mul_f32_e32 v26, v30, v26
	v_mul_f32_e32 v30, v127, v34
	v_mul_f32_e32 v30, v30, v31
	v_mul_f32_e32 v31, v124, v34
	v_exp_f32_e32 v27, v27
	v_mul_f32_e32 v28, v31, v28
	v_cvt_f32_i32_e32 v18, v18
	v_mul_f32_e32 v28, 0xbfb8aa3b, v28
	v_mul_f32_e32 v31, v125, v34
	v_exp_f32_e32 v28, v28
	v_mul_f32_e32 v29, v31, v29
	v_cvt_f32_i32_e32 v19, v19
	v_mul_f32_e32 v29, 0xbfb8aa3b, v29
	v_mul_f32_e32 v31, v120, v34
	v_add_f32_e32 v27, 1.0, v27
	v_exp_f32_e32 v29, v29
	v_mul_f32_e32 v18, v31, v18
	v_rcp_f32_e32 v27, v27
	v_mul_f32_e32 v18, 0xbfb8aa3b, v18
	v_mul_f32_e32 v31, v121, v34
	v_cvt_f32_i32_e32 v32, v32
	v_add_f32_e32 v28, 1.0, v28
	v_exp_f32_e32 v18, v18
	v_mul_f32_e32 v19, v31, v19
	v_rcp_f32_e32 v28, v28
	v_mul_f32_e32 v19, 0xbfb8aa3b, v19
	v_cvt_f32_i32_e32 v33, v33
	v_add_f32_e32 v29, 1.0, v29
	v_exp_f32_e32 v19, v19
	v_mul_f32_e32 v27, v30, v27
	v_mul_f32_e32 v30, v122, v34
	v_rcp_f32_e32 v29, v29
	v_mul_f32_e32 v30, v30, v32
	v_cvt_f32_i32_e32 v22, v22
	v_add_f32_e32 v18, 1.0, v18
	v_mul_f32_e32 v28, v30, v28
	v_mul_f32_e32 v30, v123, v34
	v_rcp_f32_e32 v18, v18
	v_mul_f32_e32 v30, v30, v33
	v_cvt_f32_i32_e32 v23, v23
	v_add_f32_e32 v19, 1.0, v19
	v_mul_f32_e32 v29, v30, v29
	v_mul_f32_e32 v30, v118, v34
	v_rcp_f32_e32 v19, v19
	v_cvt_f32_i32_e32 v20, v20
	v_mul_f32_e32 v22, v30, v22
	v_mul_f32_e32 v22, v22, v18
	v_mul_f32_e32 v18, v119, v34
	v_cvt_f32_i32_e32 v21, v21
	v_mul_f32_e32 v18, v18, v23
	v_mul_f32_e32 v23, v18, v19
	v_mul_f32_e32 v19, v116, v34
	v_mul_f32_e32 v19, v19, v20
	v_mul_f32_e32 v19, 0xbfb8aa3b, v19
	v_mul_f32_e32 v20, v117, v34
	v_exp_f32_e32 v19, v19
	v_mul_f32_e32 v20, v20, v21
	v_mul_f32_e32 v20, 0xbfb8aa3b, v20
	v_exp_f32_e32 v20, v20
	v_cvt_f32_i32_e32 v24, v24
	v_add_f32_e32 v19, 1.0, v19
	v_rcp_f32_e32 v19, v19
	v_cvt_f32_i32_e32 v25, v25
	v_add_f32_e32 v20, 1.0, v20
	v_mul_f32_e32 v18, v114, v34
	v_rcp_f32_e32 v20, v20
	v_mul_f32_e32 v18, v18, v24
	v_mul_f32_e32 v21, v18, v19
	v_mul_f32_e32 v18, v115, v34
	v_mul_f32_e32 v18, v18, v25
	s_mov_b32 s6, 0xa5000
	v_mul_f32_e32 v24, v18, v20
	v_cvt_pk_bf16_f32 v18, v26, v27
	v_cvt_pk_bf16_f32 v19, v28, v29
	v_cvt_pk_bf16_f32 v20, v22, v23
	v_add_co_u32_e32 v22, vcc, s6, v138
	v_cvt_pk_bf16_f32 v21, v21, v24
	v_cvt_f32_i32_e32 v10, v10
	s_nop 0
	v_addc_co_u32_e32 v23, vcc, 0, v139, vcc
	global_store_dwordx4 v[22:23], v[18:21], off
	ds_read_b32 v18, v158 offset:704
	v_cvt_f32_i32_e32 v14, v14
	v_cvt_f32_i32_e32 v11, v11
	v_cvt_f32_i32_e32 v15, v15
	v_cvt_f32_i32_e32 v12, v12
	s_waitcnt lgkmcnt(0)
; __device__ __forceinline__ unsigned cvt_pk_bf16(float lo, float hi) { unsigned r; asm volatile("v_cvt_pk_bf16_f32 %0, %1, %2" : "=v"(r) : "v"(lo), "v"(hi)); return r; }
; __device__ __forceinline__ float fast_sigmoid(float x) { return __builtin_amdgcn_rcpf(1.0f + __builtin_amdgcn_exp2f(-x * LOG2E)); }
; #define PG8_BAR do { if constexpr (VAR != 3) __builtin_amdgcn_s_barrier(); } while (0)
;     ...
;         if (wr == 0) PG8_BAR;
;         E(acc, cur, wr, wc, fr, fq, scr, has_next ? &nxt : nullptr);
;         if (!has_next) break;
; #pragma unroll
;         for (int a = 0; a < 2; ++a)
; #pragma unroll
;             for (int b = 0; b < 2; ++b)
; #pragma unroll
;                 for (int m = 0; m < 4; ++m)
; #pragma unroll
;                     for (int n = 0; n < 2; ++n) acc[a][b][m][n] = (f32x4){0.f, 0.f, 0.f, 0.f};
;         cur = nxt; cA = nA; cB = nB; ++ui;
;         if (wr == 1) PG8_BAR;
;     __device__ __forceinline__ void operator()(EPI_ARGS) const {
;     ...
; #pragma unroll
;             for (int ai = 0; ai < 2; ++ai)
; #pragma unroll
;                 for (int m = 0; m < 4; ++m) {
;                     const float rs = I8 ? rtab[wr * 64 + fr + ai * HALF + m * 16] : 1.0f;
;                     f32x4 o[2];
; #pragma unroll
;                     for (int n = 0; n < 2; ++n) { f32x4 a = acc[ai][0][m][n], b = acc[ai][1][m][n];
;                         if (I8) { const i32x4 ia = __builtin_bit_cast(i32x4, a), ib = __builtin_bit_cast(i32x4, b);
;                             a = (f32x4){(float)ia[0], (float)ia[1], (float)ia[2], (float)ia[3]} * (sb[0][n] * rs); b = (f32x4){(float)ib[0], (float)ib[1], (float)ib[2], (float)ib[3]} * (sb[1][n] * rs); }
; #pragma unroll
;                         for (int e = 0; e < 4; ++e) o[n][e] = glu ? a[e] * fast_sigmoid(b[e]) : a[e] * b[e]; }
;                     u32x4 w; w.x = cvt_pk_bf16(o[0][0], o[0][1]); w.y = cvt_pk_bf16(o[0][2], o[0][3]); w.z = cvt_pk_bf16(o[1][0], o[1][1]); w.w = cvt_pk_bf16(o[1][2], o[1][3]);
;                     *(u32x4*)(base + (size_t)(row0 + ai * HALF + m * 16) * CWID) = w; }
	v_mul_f32_e32 v20, v128, v18
	v_mul_f32_e32 v10, v20, v10
	v_mul_f32_e32 v10, 0xbfb8aa3b, v10
	v_exp_f32_e32 v10, v10
	v_mul_f32_e32 v19, v126, v18
	v_mul_f32_e32 v20, v129, v18
	v_mul_f32_e32 v14, v19, v14
	v_add_f32_e32 v10, 1.0, v10
	v_rcp_f32_e32 v10, v10
	v_cvt_f32_i32_e32 v13, v13
	v_mul_f32_e32 v11, v20, v11
	v_mul_f32_e32 v11, 0xbfb8aa3b, v11
	v_mul_f32_e32 v10, v14, v10
	v_mul_f32_e32 v14, v127, v18
	v_mul_f32_e32 v14, v14, v15
	v_mul_f32_e32 v15, v124, v18
	v_exp_f32_e32 v11, v11
	v_mul_f32_e32 v12, v15, v12
	v_cvt_f32_i32_e32 v2, v2
	v_mul_f32_e32 v12, 0xbfb8aa3b, v12
	v_mul_f32_e32 v15, v125, v18
	v_exp_f32_e32 v12, v12
	v_mul_f32_e32 v13, v15, v13
	v_cvt_f32_i32_e32 v3, v3
	v_mul_f32_e32 v13, 0xbfb8aa3b, v13
	v_mul_f32_e32 v15, v120, v18
	v_add_f32_e32 v11, 1.0, v11
	v_exp_f32_e32 v13, v13
	v_mul_f32_e32 v2, v15, v2
	v_rcp_f32_e32 v11, v11
	v_mul_f32_e32 v2, 0xbfb8aa3b, v2
	v_mul_f32_e32 v15, v121, v18
	v_cvt_f32_i32_e32 v16, v16
	v_add_f32_e32 v12, 1.0, v12
	v_exp_f32_e32 v2, v2
	v_mul_f32_e32 v3, v15, v3
	v_rcp_f32_e32 v12, v12
	v_mul_f32_e32 v3, 0xbfb8aa3b, v3
	v_cvt_f32_i32_e32 v17, v17
	v_add_f32_e32 v13, 1.0, v13
	v_exp_f32_e32 v3, v3
	v_mul_f32_e32 v11, v14, v11
	v_mul_f32_e32 v14, v122, v18
	v_rcp_f32_e32 v13, v13
	v_mul_f32_e32 v14, v14, v16
	v_cvt_f32_i32_e32 v6, v6
	v_add_f32_e32 v2, 1.0, v2
	v_mul_f32_e32 v12, v14, v12
	v_mul_f32_e32 v14, v123, v18
	v_rcp_f32_e32 v2, v2
	v_mul_f32_e32 v14, v14, v17
	v_cvt_f32_i32_e32 v7, v7
	v_add_f32_e32 v3, 1.0, v3
	v_mul_f32_e32 v13, v14, v13
	v_mul_f32_e32 v14, v118, v18
	v_rcp_f32_e32 v3, v3
	v_cvt_f32_i32_e32 v4, v4
	v_mul_f32_e32 v6, v14, v6
	v_mul_f32_e32 v6, v6, v2
	v_mul_f32_e32 v2, v119, v18
	v_cvt_f32_i32_e32 v5, v5
	v_mul_f32_e32 v2, v2, v7
	v_mul_f32_e32 v7, v2, v3
	v_mul_f32_e32 v3, v116, v18
	v_mul_f32_e32 v3, v3, v4
	v_mul_f32_e32 v3, 0xbfb8aa3b, v3
	v_mul_f32_e32 v4, v117, v18
	v_exp_f32_e32 v3, v3
	v_mul_f32_e32 v4, v4, v5
	v_mul_f32_e32 v4, 0xbfb8aa3b, v4
	v_exp_f32_e32 v4, v4
	v_cvt_f32_i32_e32 v8, v8
	v_add_f32_e32 v3, 1.0, v3
	v_rcp_f32_e32 v3, v3
	v_cvt_f32_i32_e32 v9, v9
	v_add_f32_e32 v4, 1.0, v4
	v_mul_f32_e32 v2, v114, v18
	v_rcp_f32_e32 v4, v4
	v_mul_f32_e32 v2, v2, v8
	v_mul_f32_e32 v5, v2, v3
	v_mul_f32_e32 v2, v115, v18
	v_mul_f32_e32 v2, v2, v9
	v_mul_f32_e32 v8, v2, v4
	v_cvt_pk_bf16_f32 v2, v10, v11
	v_cvt_pk_bf16_f32 v3, v12, v13
	v_cvt_pk_bf16_f32 v4, v6, v7
	v_add_co_u32_e32 v6, vcc, 0xb5800, v138
	v_readlane_b32 s37, v244, 3
	s_nop 0
	v_addc_co_u32_e32 v7, vcc, 0, v139, vcc
	s_andn2_b64 vcc, exec, s[4:5]
	s_mov_b64 s[4:5], -1
	v_readlane_b32 s38, v244, 4
	v_readlane_b32 s39, v244, 5
	v_readlane_b32 s40, v244, 6
	v_readlane_b32 s41, v244, 7
	v_readlane_b32 s42, v244, 8
	v_readlane_b32 s43, v244, 9
	v_readlane_b32 s44, v244, 10
	v_readlane_b32 s45, v244, 11
	v_readlane_b32 s46, v244, 12
	v_readlane_b32 s47, v244, 13
	v_readlane_b32 s50, v244, 16
	v_readlane_b32 s51, v244, 17
	v_cvt_pk_bf16_f32 v5, v5, v8
	global_store_dwordx4 v[6:7], v[2:5], off
	s_cbranch_vccnz .LBB0_531
	s_andn2_b64 vcc, exec, s[60:61]
	s_cbranch_vccnz .LBB0_530
	s_barrier
	s_branch .LBB0_530

; #define GAS __attribute__((address_space(1)))
; __device__ __forceinline__ void conv_a_wave(const bf16* U0, const float* cwp, const float* cb, const float* lg, const float* lb, bf16* MIX, LAS unsigned* T, int it0, int step, int nitems, int lane) {
;     ...
;     for (int item = it0; item < nitems; item += step) {
;         const int tb = item >> 4, grp = item & 15, r0 = tb * 32; const bool first = (r0 % SEQ) == 0;
;         u32x4 v[16];
; #pragma unroll
;         for (int p = 0; p < 16; ++p) { const int rr = 4 * p + lr; v[p] = (u32x4){0u, 0u, 0u, 0u};
;             if (rr < 62 && !(first && rr < 30)) v[p] = *(const GAS u32x4*)(U0 + (size_t)(r0 - 30 + rr) * CWID + grp * 128 + lc * 8); }
.LBB0_630:
	s_and_b32 s6, s26, 15
	s_and_b32 s66, s14, 0xffffffe0
	s_and_b32 s0, s26, 0x7f0
	s_cmp_lg_u32 s0, 0
	s_cselect_b64 s[0:1], -1, 0
	s_lshl_b32 s54, s6, 8
	s_sub_i32 s7, s66, 30
	v_lshl_add_u64 v[146:147], v[66:67], 0, s[54:55]
	s_and_b64 vcc, exec, s[0:1]
	s_cbranch_vccz .LBB0_632
	v_add_u32_e32 v2, s7, v148
	v_ashrrev_i32_e32 v3, 31, v2
	v_mul_u32_u24_e32 v2, 0x1080, v2
	v_mov_b32_e32 v3, 0
	v_lshl_add_u64 v[2:3], v[146:147], 0, v[2:3]
	global_load_dwordx4 v[2:5], v[2:3], off
	s_branch .LBB0_633

; #define GAS __attribute__((address_space(1)))
; __device__ __forceinline__ void conv_a_wave(const bf16* U0, const float* cwp, const float* cb, const float* lg, const float* lb, bf16* MIX, LAS unsigned* T, int it0, int step, int nitems, int lane) {
;     ...
;     for (int item = it0; item < nitems; item += step) {
;         const int tb = item >> 4, grp = item & 15, r0 = tb * 32; const bool first = (r0 % SEQ) == 0;
;         u32x4 v[16];
; #pragma unroll
;         for (int p = 0; p < 16; ++p) { const int rr = 4 * p + lr; v[p] = (u32x4){0u, 0u, 0u, 0u};
;             if (rr < 62 && !(first && rr < 30)) v[p] = *(const GAS u32x4*)(U0 + (size_t)(r0 - 30 + rr) * CWID + grp * 128 + lc * 8); }
.LBB0_633:
	v_cndmask_b32_e64 v7, 0, 1, s[0:1]
	v_mov_b32_e32 v6, 0
	v_cmp_ne_u32_e64 s[4:5], 1, v7
	s_andn2_b64 vcc, exec, s[0:1]
	v_mov_b32_e32 v10, 0
	v_mov_b32_e32 v11, 0
	v_mov_b32_e32 v12, 0
	v_mov_b32_e32 v13, 0
	s_cbranch_vccnz .LBB0_635
	v_add_u32_e32 v8, s7, v150
	v_ashrrev_i32_e32 v9, 31, v8
	v_mul_u32_u24_e32 v8, 0x1080, v8
	v_mov_b32_e32 v9, 0
	v_lshl_add_u64 v[8:9], v[146:147], 0, v[8:9]
	global_load_dwordx4 v[10:13], v[8:9], off
.LBB0_635:
	s_and_b64 vcc, exec, s[4:5]
	v_mov_b32_e32 v7, 0
	v_mov_b32_e32 v8, 0
	v_mov_b32_e32 v9, 0
	s_cbranch_vccnz .LBB0_637
	v_add_u32_e32 v6, s7, v151
	v_ashrrev_i32_e32 v7, 31, v6
	v_mul_u32_u24_e32 v6, 0x1080, v6
	v_mov_b32_e32 v7, 0
	v_lshl_add_u64 v[6:7], v[146:147], 0, v[6:7]
	global_load_dwordx4 v[6:9], v[6:7], off
.LBB0_637:
	v_mov_b32_e32 v14, 0
	s_and_b64 vcc, exec, s[4:5]
	v_mov_b32_e32 v18, 0
	v_mov_b32_e32 v19, 0
	v_mov_b32_e32 v20, 0
	v_mov_b32_e32 v21, 0
	s_cbranch_vccnz .LBB0_639
	v_add_u32_e32 v16, s7, v152
	v_ashrrev_i32_e32 v17, 31, v16
	v_mul_u32_u24_e32 v16, 0x1080, v16
	v_mov_b32_e32 v17, 0
	v_lshl_add_u64 v[16:17], v[146:147], 0, v[16:17]
	global_load_dwordx4 v[18:21], v[16:17], off
.LBB0_639:
	s_and_b64 vcc, exec, s[4:5]
	v_mov_b32_e32 v15, 0
	v_mov_b32_e32 v16, 0
	v_mov_b32_e32 v17, 0
	s_cbranch_vccnz .LBB0_641
	v_add_u32_e32 v14, s7, v153
	v_ashrrev_i32_e32 v15, 31, v14
	v_mul_u32_u24_e32 v14, 0x1080, v14
	v_mov_b32_e32 v15, 0
	v_lshl_add_u64 v[14:15], v[146:147], 0, v[14:15]
	global_load_dwordx4 v[14:17], v[14:15], off
.LBB0_641:
	s_waitcnt vmcnt(40)
	v_mov_b32_e32 v22, 0
	s_and_b64 vcc, exec, s[4:5]
	s_waitcnt vmcnt(39)
	v_mov_b32_e32 v26, 0
	v_mov_b32_e32 v27, 0
	v_mov_b32_e32 v28, 0
	v_mov_b32_e32 v29, 0
	s_cbranch_vccnz .LBB0_643
	v_add_u32_e32 v24, s7, v154
	v_ashrrev_i32_e32 v25, 31, v24
	v_mul_u32_u24_e32 v24, 0x1080, v24
	v_mov_b32_e32 v25, 0
	v_lshl_add_u64 v[24:25], v[146:147], 0, v[24:25]
	global_load_dwordx4 v[26:29], v[24:25], off
.LBB0_643:
	s_and_b64 vcc, exec, s[4:5]
	s_mov_b64 s[0:1], s[64:65]
	v_mov_b32_e32 v23, 0
	v_mov_b32_e32 v24, 0
	v_mov_b32_e32 v25, 0
	s_cbranch_vccnz .LBB0_645
	v_add_u32_e32 v22, s7, v155
	v_ashrrev_i32_e32 v23, 31, v22
	v_mul_u32_u24_e32 v22, 0x1080, v22
	v_mov_b32_e32 v23, 0
	v_lshl_add_u64 v[22:23], v[146:147], 0, v[22:23]
	global_load_dwordx4 v[22:25], v[22:23], off
	s_andn2_b64 s[0:1], s[64:65], exec
.LBB0_645:
	s_xor_b64 s[4:5], s[0:1], -1
	v_mov_b32_e32 v30, 0
	s_waitcnt vmcnt(38)
	v_mov_b32_e32 v34, 0
	v_mov_b32_e32 v35, 0
	v_mov_b32_e32 v36, 0
	v_mov_b32_e32 v37, 0
	s_and_saveexec_b64 s[0:1], s[4:5]
	s_cbranch_execz .LBB0_647
	v_add_u32_e32 v32, s7, v156
	v_ashrrev_i32_e32 v33, 31, v32
	v_mul_u32_u24_e32 v32, 0x1080, v32
	v_mov_b32_e32 v33, 0
	v_lshl_add_u64 v[32:33], v[146:147], 0, v[32:33]
	global_load_dwordx4 v[34:37], v[32:33], off
.LBB0_647:
	s_or_b64 exec, exec, s[0:1]
	v_add_u32_e32 v32, s7, v157
	v_add_u32_e32 v38, s7, v158
	v_ashrrev_i32_e32 v33, 31, v32
	v_ashrrev_i32_e32 v39, 31, v38
	v_mul_u32_u24_e32 v32, 0x1080, v32
	v_mov_b32_e32 v33, 0
	v_mul_u32_u24_e32 v38, 0x1080, v38
	v_mov_b32_e32 v39, 0
	v_lshl_add_u64 v[32:33], v[146:147], 0, v[32:33]
	s_waitcnt vmcnt(36)
	v_lshl_add_u64 v[42:43], v[146:147], 0, v[38:39]
	global_load_dwordx4 v[38:41], v[32:33], off
	s_nop 0
	global_load_dwordx4 v[42:45], v[42:43], off
	v_add_u32_e32 v32, s7, v159
	v_add_u32_e32 v46, s7, v160
	v_ashrrev_i32_e32 v33, 31, v32
	v_ashrrev_i32_e32 v47, 31, v46
	v_mul_u32_u24_e32 v32, 0x1080, v32
	v_mov_b32_e32 v33, 0
	v_mul_u32_u24_e32 v46, 0x1080, v46
	v_mov_b32_e32 v47, 0
	v_lshl_add_u64 v[32:33], v[146:147], 0, v[32:33]
	s_waitcnt vmcnt(37)
	v_lshl_add_u64 v[50:51], v[146:147], 0, v[46:47]
	global_load_dwordx4 v[46:49], v[32:33], off
	s_nop 0
	global_load_dwordx4 v[50:53], v[50:51], off
	v_add_u32_e32 v32, s7, v161
	s_waitcnt vmcnt(38)
	v_add_u32_e32 v54, s7, v162
	v_ashrrev_i32_e32 v33, 31, v32
	v_ashrrev_i32_e32 v55, 31, v54
	v_mul_u32_u24_e32 v32, 0x1080, v32
	v_mov_b32_e32 v33, 0
	v_mul_u32_u24_e32 v54, 0x1080, v54
	v_mov_b32_e32 v55, 0
	v_lshl_add_u64 v[32:33], v[146:147], 0, v[32:33]
	s_waitcnt vmcnt(36)
	v_lshl_add_u64 v[58:59], v[146:147], 0, v[54:55]
	global_load_dwordx4 v[54:57], v[32:33], off
	s_nop 0
	global_load_dwordx4 v[58:61], v[58:59], off
	v_add_u32_e32 v32, s7, v163
	v_ashrrev_i32_e32 v33, 31, v32
	v_mul_u32_u24_e32 v32, 0x1080, v32
	v_mov_b32_e32 v33, 0
	v_lshl_add_u64 v[32:33], v[146:147], 0, v[32:33]
	global_load_dwordx4 v[62:65], v[32:33], off
	v_mov_b32_e32 v31, 0
	v_mov_b32_e32 v32, 0
	v_mov_b32_e32 v33, 0
	s_and_saveexec_b64 s[0:1], s[2:3]
	s_cbranch_execz .LBB0_649
	v_add_u32_e32 v30, s7, v164
	v_ashrrev_i32_e32 v31, 31, v30
	v_mul_u32_u24_e32 v30, 0x1080, v30
	v_mov_b32_e32 v31, 0
	v_lshl_add_u64 v[30:31], v[146:147], 0, v[30:31]
	global_load_dwordx4 v[30:33], v[30:31], off
